# T21: attn_c item epilogue stores widened to dwordx4 via v_permlane16_swap row exchange (8 stores instead of 16 per item half-pair)
# speedup vs baseline: 1.0066x; 1.0012x over previous
; DI float bflo(unsigned v) { return __uint_as_float(v << 16); }
; DI float bfhi(unsigned v) { return __uint_as_float(v & 0xffff0000u); }
; DI void attn_c_item(const Params& P, int l, int b, int h, int qb, char* shm, float B2, int dry) {
;     ...
;   u16* actC = (u16*)(P.ws + OFF_ACTC);
; #pragma unroll
;   for (int qs = 0; qs < 2; ++qs) {
;     float lt = lsum[qs];
;     lt += __shfl_xor(lt, 16);
;     lt += __shfl_xor(lt, 32);
;     const float inv = 1.f / lt;
;     u16* dp = actC + (size_t)(b * SEQ + q0 + qs * 16 + fr) * 512 + h * 128 + fq * 4;
; #pragma unroll
;     for (int dvs = 0; dvs < 8; ++dvs) {
;       u32x2 gz = *(const u32x2*)(dp + dvs * 16);
;       u32x2 ov = {pack2(o[dvs][qs][0] * inv * bflo(gz[0]), o[dvs][qs][1] * inv * bfhi(gz[0])),
;                   pack2(o[dvs][qs][2] * inv * bflo(gz[1]), o[dvs][qs][3] * inv * bfhi(gz[1]))};
;       if (!dry) *(u32x2*)(dp + dvs * 16) = ov;
;     }
;   }
.LBB0_580:
	s_waitcnt vmcnt(0)
	v_add_u32_e32 v122, 0x3000, v122
	v_add_u32_e32 v123, 0x3000, v123
	v_add_u32_e32 v124, 0x3000, v124
	v_add_u32_e32 v125, 64, v125
	s_cmp_lg_u32 s0, s35
	v_add_u32_e32 v126, 64, v126
	s_waitcnt vmcnt(0) lgkmcnt(0)
	s_barrier
	s_cbranch_scc1 .LBB0_576
	ds_bpermute_b32 v32, v212, v119
	v_lshlrev_b32_e32 v132, 1, v116
	v_lshl_add_u64 v[34:35], s[18:19], 0, v[132:133]
	s_waitcnt lgkmcnt(0)
	v_add_f32_e32 v32, v119, v32
	ds_bpermute_b32 v33, v211, v32
	s_waitcnt lgkmcnt(0)
	v_add_f32_e32 v32, v32, v33
	v_div_scale_f32 v33, s[0:1], v32, v32, 1.0
	v_rcp_f32_e32 v36, v33
	s_nop 0
	v_fma_f32 v37, -v33, v36, 1.0
	v_fmac_f32_e32 v36, v37, v36
	v_div_scale_f32 v37, vcc, 1.0, v32, 1.0
	v_mul_f32_e32 v38, v37, v36
	v_fma_f32 v39, -v33, v38, v37
	v_fmac_f32_e32 v38, v39, v36
	v_fma_f32 v33, -v33, v38, v37
	v_div_fmas_f32 v33, v33, v36, v38
	v_lshlrev_b64 v[36:37], 10, v[114:115]
	v_lshl_add_u64 v[36:37], v[34:35], 0, v[36:37]
	global_load_dwordx2 v[230:231], v[36:37], off
	global_load_dwordx2 v[232:233], v[36:37], off offset:32
	global_load_dwordx2 v[234:235], v[36:37], off offset:64
	global_load_dwordx2 v[236:237], v[36:37], off offset:96
	global_load_dwordx2 v[238:239], v[36:37], off offset:128
	global_load_dwordx2 v[240:241], v[36:37], off offset:160
	global_load_dwordx2 v[242:243], v[36:37], off offset:192
	global_load_dwordx2 v[244:245], v[36:37], off offset:224
	v_mbcnt_lo_u32_b32 v250, -1, 0
	v_mbcnt_hi_u32_b32 v250, -1, v250
	v_bfe_u32 v250, v250, 4, 1
	v_mul_u32_u24_e32 v250, 24, v250
	v_mov_b32_e32 v251, 0
	v_lshl_add_u64 v[250:251], v[36:37], 0, v[250:251]
	v_div_fixup_f32 v32, v33, v32, 1.0
	v_pk_mul_f32 v[44:45], v[104:105], v[32:33] op_sel_hi:[1,0]
	v_pk_mul_f32 v[40:41], v[40:41], v[32:33] op_sel_hi:[1,0]
	s_waitcnt vmcnt(7) lgkmcnt(0)
	v_lshlrev_b32_e32 v46, 16, v230
	v_and_b32_e32 v47, 0xffff0000, v230
	v_pk_mul_f32 v[44:45], v[44:45], v[46:47]
	v_lshlrev_b32_e32 v46, 16, v231
	v_cvt_pk_bf16_f32 v246, v44, v45
	v_pk_mul_f32 v[44:45], v[106:107], v[32:33] op_sel_hi:[1,0]
	v_and_b32_e32 v47, 0xffff0000, v231
	v_pk_mul_f32 v[44:45], v[44:45], v[46:47]
	s_nop 0
	v_cvt_pk_bf16_f32 v247, v44, v45
	v_pk_mul_f32 v[44:45], v[96:97], v[32:33] op_sel_hi:[1,0]
	s_waitcnt vmcnt(6) lgkmcnt(0)
	v_lshlrev_b32_e32 v46, 16, v232
	v_and_b32_e32 v47, 0xffff0000, v232
	v_pk_mul_f32 v[44:45], v[44:45], v[46:47]
	v_lshlrev_b32_e32 v46, 16, v233
	v_cvt_pk_bf16_f32 v248, v44, v45
	v_pk_mul_f32 v[44:45], v[98:99], v[32:33] op_sel_hi:[1,0]
	v_and_b32_e32 v47, 0xffff0000, v233
	v_pk_mul_f32 v[44:45], v[44:45], v[46:47]
	s_nop 0
	v_cvt_pk_bf16_f32 v249, v44, v45
	s_nop 1
	v_permlane16_swap_b32_e32 v246, v248
	v_permlane16_swap_b32_e32 v247, v249
	global_store_dwordx4 v[250:251], v[246:249], off
	v_pk_mul_f32 v[44:45], v[92:93], v[32:33] op_sel_hi:[1,0]
	s_waitcnt vmcnt(6) lgkmcnt(0)
	v_lshlrev_b32_e32 v46, 16, v234
	v_and_b32_e32 v47, 0xffff0000, v234
	v_pk_mul_f32 v[44:45], v[44:45], v[46:47]
	v_lshlrev_b32_e32 v46, 16, v235
	v_cvt_pk_bf16_f32 v246, v44, v45
	v_pk_mul_f32 v[44:45], v[94:95], v[32:33] op_sel_hi:[1,0]
	v_and_b32_e32 v47, 0xffff0000, v235
	v_pk_mul_f32 v[44:45], v[44:45], v[46:47]
	s_nop 0
	v_cvt_pk_bf16_f32 v247, v44, v45
	v_pk_mul_f32 v[44:45], v[72:73], v[32:33] op_sel_hi:[1,0]
	s_waitcnt vmcnt(5) lgkmcnt(0)
	v_lshlrev_b32_e32 v46, 16, v236
	v_and_b32_e32 v47, 0xffff0000, v236
	v_pk_mul_f32 v[44:45], v[44:45], v[46:47]
	v_lshlrev_b32_e32 v46, 16, v237
	v_cvt_pk_bf16_f32 v248, v44, v45
	v_pk_mul_f32 v[44:45], v[74:75], v[32:33] op_sel_hi:[1,0]
	v_and_b32_e32 v47, 0xffff0000, v237
	v_pk_mul_f32 v[44:45], v[44:45], v[46:47]
	s_nop 0
	v_cvt_pk_bf16_f32 v249, v44, v45
	s_nop 1
	v_permlane16_swap_b32_e32 v246, v248
	v_permlane16_swap_b32_e32 v247, v249
	global_store_dwordx4 v[250:251], v[246:249], off offset:64
	v_pk_mul_f32 v[44:45], v[64:65], v[32:33] op_sel_hi:[1,0]
	s_waitcnt vmcnt(5) lgkmcnt(0)
	v_lshlrev_b32_e32 v46, 16, v238
	v_and_b32_e32 v47, 0xffff0000, v238
	v_pk_mul_f32 v[44:45], v[44:45], v[46:47]
	v_lshlrev_b32_e32 v46, 16, v239
	v_cvt_pk_bf16_f32 v246, v44, v45
	v_pk_mul_f32 v[44:45], v[66:67], v[32:33] op_sel_hi:[1,0]
	v_and_b32_e32 v47, 0xffff0000, v239
	v_pk_mul_f32 v[44:45], v[44:45], v[46:47]
	s_nop 0
	v_cvt_pk_bf16_f32 v247, v44, v45
	v_pk_mul_f32 v[44:45], v[52:53], v[32:33] op_sel_hi:[1,0]
	s_waitcnt vmcnt(4) lgkmcnt(0)
	v_lshlrev_b32_e32 v46, 16, v240
	v_and_b32_e32 v47, 0xffff0000, v240
	v_pk_mul_f32 v[44:45], v[44:45], v[46:47]
	v_lshlrev_b32_e32 v46, 16, v241
	v_cvt_pk_bf16_f32 v248, v44, v45
	v_pk_mul_f32 v[44:45], v[54:55], v[32:33] op_sel_hi:[1,0]
	v_and_b32_e32 v47, 0xffff0000, v241
	v_pk_mul_f32 v[44:45], v[44:45], v[46:47]
	s_nop 0
	v_cvt_pk_bf16_f32 v249, v44, v45
	s_nop 1
	v_permlane16_swap_b32_e32 v246, v248
	v_permlane16_swap_b32_e32 v247, v249
	global_store_dwordx4 v[250:251], v[246:249], off offset:128
	v_pk_mul_f32 v[44:45], v[48:49], v[32:33] op_sel_hi:[1,0]
	s_waitcnt vmcnt(4) lgkmcnt(0)
	v_lshlrev_b32_e32 v46, 16, v242
	v_and_b32_e32 v47, 0xffff0000, v242
	v_pk_mul_f32 v[44:45], v[44:45], v[46:47]
	v_lshlrev_b32_e32 v46, 16, v243
	v_cvt_pk_bf16_f32 v246, v44, v45
	v_pk_mul_f32 v[44:45], v[50:51], v[32:33] op_sel_hi:[1,0]
	v_and_b32_e32 v47, 0xffff0000, v243
	v_pk_mul_f32 v[44:45], v[44:45], v[46:47]
	v_pk_mul_f32 v[32:33], v[42:43], v[32:33] op_sel_hi:[1,0]
	v_cvt_pk_bf16_f32 v247, v44, v45
	s_waitcnt vmcnt(3) lgkmcnt(0)
	v_lshlrev_b32_e32 v44, 16, v244
	v_and_b32_e32 v45, 0xffff0000, v244
	v_pk_mul_f32 v[40:41], v[40:41], v[44:45]
	s_nop 0
	v_cvt_pk_bf16_f32 v248, v40, v41
	v_lshlrev_b32_e32 v40, 16, v245
	v_and_b32_e32 v41, 0xffff0000, v245
	v_pk_mul_f32 v[32:33], v[32:33], v[40:41]
	s_nop 0
	v_cvt_pk_bf16_f32 v249, v32, v33
	ds_bpermute_b32 v32, v212, v118
	s_nop 1
	v_permlane16_swap_b32_e32 v246, v248
	v_permlane16_swap_b32_e32 v247, v249
	global_store_dwordx4 v[250:251], v[246:249], off offset:192
	s_waitcnt lgkmcnt(0)
; DI float bflo(unsigned v) { return __uint_as_float(v << 16); }
; DI float bfhi(unsigned v) { return __uint_as_float(v & 0xffff0000u); }
; DI void attn_c_item(const Params& P, int l, int b, int h, int qb, char* shm, float B2, int dry) {
;     ...
;   u16* actC = (u16*)(P.ws + OFF_ACTC);
; #pragma unroll
;   for (int qs = 0; qs < 2; ++qs) {
;     float lt = lsum[qs];
;     lt += __shfl_xor(lt, 16);
;     lt += __shfl_xor(lt, 32);
;     const float inv = 1.f / lt;
;     u16* dp = actC + (size_t)(b * SEQ + q0 + qs * 16 + fr) * 512 + h * 128 + fq * 4;
; #pragma unroll
;     for (int dvs = 0; dvs < 8; ++dvs) {
;       u32x2 gz = *(const u32x2*)(dp + dvs * 16);
;       u32x2 ov = {pack2(o[dvs][qs][0] * inv * bflo(gz[0]), o[dvs][qs][1] * inv * bfhi(gz[0])),
;                   pack2(o[dvs][qs][2] * inv * bflo(gz[1]), o[dvs][qs][3] * inv * bfhi(gz[1]))};
;       if (!dry) *(u32x2*)(dp + dvs * 16) = ov;
;     }
;   }
; DI void phase_attn_c(const Params& P, int l, char* shm, int dry) {
;     ...
;   for (int it = blockIdx.x; it < 256; it += gridDim.x) {
;     const int bh = it >> 4, pr = it & 15, b = bh >> 2, h = bh & 3;
; #pragma clang loop unroll(disable)
;     for (int hf = 0; hf < 2; ++hf) attn_c_item(P, l, b, h, hf ? pr : 31 - pr, shm, B2, dry);
	v_add_f32_e32 v32, v118, v32
	ds_bpermute_b32 v33, v211, v32
	s_waitcnt lgkmcnt(0)
	v_add_f32_e32 v32, v32, v33
	v_div_scale_f32 v33, s[0:1], v32, v32, 1.0
	v_rcp_f32_e32 v36, v33
	s_mov_b64 s[0:1], 0
	v_fma_f32 v37, -v33, v36, 1.0
	v_fmac_f32_e32 v36, v37, v36
	v_div_scale_f32 v37, vcc, 1.0, v32, 1.0
	v_mul_f32_e32 v38, v37, v36
	v_fma_f32 v39, -v33, v38, v37
	v_fmac_f32_e32 v38, v39, v36
	v_fma_f32 v33, -v33, v38, v37
	v_div_fmas_f32 v33, v33, v36, v38
	v_lshlrev_b64 v[36:37], 10, v[112:113]
	v_lshl_add_u64 v[34:35], v[34:35], 0, v[36:37]
	global_load_dwordx2 v[230:231], v[34:35], off
	global_load_dwordx2 v[232:233], v[34:35], off offset:32
	global_load_dwordx2 v[234:235], v[34:35], off offset:64
	global_load_dwordx2 v[236:237], v[34:35], off offset:96
	global_load_dwordx2 v[238:239], v[34:35], off offset:128
	global_load_dwordx2 v[240:241], v[34:35], off offset:160
	global_load_dwordx2 v[242:243], v[34:35], off offset:192
	global_load_dwordx2 v[244:245], v[34:35], off offset:224
	v_mbcnt_lo_u32_b32 v250, -1, 0
	v_mbcnt_hi_u32_b32 v250, -1, v250
	v_bfe_u32 v250, v250, 4, 1
	v_mul_u32_u24_e32 v250, 24, v250
	v_mov_b32_e32 v251, 0
	v_lshl_add_u64 v[250:251], v[34:35], 0, v[250:251]
	v_div_fixup_f32 v32, v33, v32, 1.0
	v_pk_mul_f32 v[28:29], v[28:29], v[32:33] op_sel_hi:[1,0]
	v_pk_mul_f32 v[30:31], v[30:31], v[32:33] op_sel_hi:[1,0]
	v_pk_mul_f32 v[24:25], v[24:25], v[32:33] op_sel_hi:[1,0]
	v_pk_mul_f32 v[26:27], v[26:27], v[32:33] op_sel_hi:[1,0]
	v_pk_mul_f32 v[20:21], v[20:21], v[32:33] op_sel_hi:[1,0]
	v_pk_mul_f32 v[22:23], v[22:23], v[32:33] op_sel_hi:[1,0]
	v_pk_mul_f32 v[16:17], v[16:17], v[32:33] op_sel_hi:[1,0]
	v_pk_mul_f32 v[18:19], v[18:19], v[32:33] op_sel_hi:[1,0]
	v_pk_mul_f32 v[12:13], v[12:13], v[32:33] op_sel_hi:[1,0]
	v_pk_mul_f32 v[14:15], v[14:15], v[32:33] op_sel_hi:[1,0]
	v_pk_mul_f32 v[8:9], v[8:9], v[32:33] op_sel_hi:[1,0]
	v_pk_mul_f32 v[10:11], v[10:11], v[32:33] op_sel_hi:[1,0]
	v_pk_mul_f32 v[4:5], v[4:5], v[32:33] op_sel_hi:[1,0]
	v_pk_mul_f32 v[6:7], v[6:7], v[32:33] op_sel_hi:[1,0]
	v_pk_mul_f32 v[0:1], v[0:1], v[32:33] op_sel_hi:[1,0]
	v_pk_mul_f32 v[2:3], v[2:3], v[32:33] op_sel_hi:[1,0]
	s_and_b64 vcc, exec, s[20:21]
	s_waitcnt vmcnt(7) lgkmcnt(0)
	v_lshlrev_b32_e32 v38, 16, v230
	v_and_b32_e32 v39, 0xffff0000, v230
	v_lshlrev_b32_e32 v36, 16, v231
	v_and_b32_e32 v37, 0xffff0000, v231
	v_pk_mul_f32 v[28:29], v[28:29], v[38:39]
	v_pk_mul_f32 v[30:31], v[30:31], v[36:37]
	v_cvt_pk_bf16_f32 v246, v28, v29
	v_cvt_pk_bf16_f32 v247, v30, v31
	s_waitcnt vmcnt(6) lgkmcnt(0)
	v_lshlrev_b32_e32 v30, 16, v232
	v_and_b32_e32 v31, 0xffff0000, v232
	v_lshlrev_b32_e32 v28, 16, v233
	v_and_b32_e32 v29, 0xffff0000, v233
	v_pk_mul_f32 v[24:25], v[24:25], v[30:31]
	v_pk_mul_f32 v[26:27], v[26:27], v[28:29]
	v_cvt_pk_bf16_f32 v248, v24, v25
	v_cvt_pk_bf16_f32 v249, v26, v27
	s_nop 1
	v_permlane16_swap_b32_e32 v246, v248
	v_permlane16_swap_b32_e32 v247, v249
	global_store_dwordx4 v[250:251], v[246:249], off
	s_waitcnt vmcnt(6) lgkmcnt(0)
	v_lshlrev_b32_e32 v26, 16, v234
	v_and_b32_e32 v27, 0xffff0000, v234
	v_lshlrev_b32_e32 v24, 16, v235
	v_and_b32_e32 v25, 0xffff0000, v235
	v_pk_mul_f32 v[20:21], v[20:21], v[26:27]
	v_pk_mul_f32 v[22:23], v[22:23], v[24:25]
	v_cvt_pk_bf16_f32 v246, v20, v21
	v_cvt_pk_bf16_f32 v247, v22, v23
	s_waitcnt vmcnt(5) lgkmcnt(0)
	v_lshlrev_b32_e32 v22, 16, v236
	v_and_b32_e32 v23, 0xffff0000, v236
	v_lshlrev_b32_e32 v20, 16, v237
	v_and_b32_e32 v21, 0xffff0000, v237
	v_pk_mul_f32 v[16:17], v[16:17], v[22:23]
	v_pk_mul_f32 v[18:19], v[18:19], v[20:21]
	v_cvt_pk_bf16_f32 v248, v16, v17
	v_cvt_pk_bf16_f32 v249, v18, v19
	s_nop 1
	v_permlane16_swap_b32_e32 v246, v248
	v_permlane16_swap_b32_e32 v247, v249
	global_store_dwordx4 v[250:251], v[246:249], off offset:64
	s_waitcnt vmcnt(5) lgkmcnt(0)
	v_lshlrev_b32_e32 v18, 16, v238
	v_and_b32_e32 v19, 0xffff0000, v238
	v_lshlrev_b32_e32 v16, 16, v239
	v_and_b32_e32 v17, 0xffff0000, v239
	v_pk_mul_f32 v[12:13], v[12:13], v[18:19]
	v_pk_mul_f32 v[14:15], v[14:15], v[16:17]
	v_cvt_pk_bf16_f32 v246, v12, v13
	v_cvt_pk_bf16_f32 v247, v14, v15
	s_waitcnt vmcnt(4) lgkmcnt(0)
	v_lshlrev_b32_e32 v14, 16, v240
	v_and_b32_e32 v15, 0xffff0000, v240
	v_lshlrev_b32_e32 v12, 16, v241
	v_and_b32_e32 v13, 0xffff0000, v241
	v_pk_mul_f32 v[8:9], v[8:9], v[14:15]
	v_pk_mul_f32 v[10:11], v[10:11], v[12:13]
	v_cvt_pk_bf16_f32 v248, v8, v9
	v_cvt_pk_bf16_f32 v249, v10, v11
	s_nop 1
	v_permlane16_swap_b32_e32 v246, v248
	v_permlane16_swap_b32_e32 v247, v249
	global_store_dwordx4 v[250:251], v[246:249], off offset:128
	s_waitcnt vmcnt(4) lgkmcnt(0)
	v_lshlrev_b32_e32 v10, 16, v242
	v_and_b32_e32 v11, 0xffff0000, v242
	v_lshlrev_b32_e32 v8, 16, v243
	v_and_b32_e32 v9, 0xffff0000, v243
	v_pk_mul_f32 v[4:5], v[4:5], v[10:11]
	v_pk_mul_f32 v[6:7], v[6:7], v[8:9]
	v_cvt_pk_bf16_f32 v246, v4, v5
	v_cvt_pk_bf16_f32 v247, v6, v7
	s_waitcnt vmcnt(3) lgkmcnt(0)
	v_lshlrev_b32_e32 v6, 16, v244
	v_and_b32_e32 v7, 0xffff0000, v244
	v_lshlrev_b32_e32 v4, 16, v245
	v_and_b32_e32 v5, 0xffff0000, v245
	v_pk_mul_f32 v[0:1], v[0:1], v[6:7]
	v_pk_mul_f32 v[2:3], v[2:3], v[4:5]
	v_cvt_pk_bf16_f32 v248, v0, v1
	v_cvt_pk_bf16_f32 v249, v2, v3
	s_nop 1
	v_permlane16_swap_b32_e32 v246, v248
	v_permlane16_swap_b32_e32 v247, v249
	global_store_dwordx4 v[250:251], v[246:249], off offset:192
	s_cbranch_vccz .LBB0_575
	s_add_i32 s28, s28, s72
	s_cmpk_gt_i32 s28, 0xff
	s_cbranch_scc0 .LBB0_574
	v_readlane_b32 s50, v252, 18
	v_readlane_b32 s51, v252, 19
	s_movk_i32 s42, 0xfc0
	v_readlane_b32 s46, v252, 31
	s_mov_b64 s[34:35], 0x20000
	s_mov_b64 s[36:37], 0x8000
	s_mov_b64 s[38:39], 0x18000
